# attention unit epilogue: IEEE f32 division expansions of the silu gate replaced by v_rcp_f32 (as in S3/GLU epilogues); on top of v111
# speedup vs baseline: 1.0150x; 1.0023x over previous
; #define LAS __attribute__((address_space(3)))
; __device__ __forceinline__ unsigned cvtpk_s(float lo, float hi) { f32x2_t v = {lo, hi}; bf16x2_t b = __builtin_convertvector(v, bf16x2_t); return __builtin_bit_cast(unsigned, b); }
; #define ATT_GD(ms, dvb) do { \
;         const v4i16_t lo_ = ATT_VTR(vb_ + (ms) * 16 * 320 + (dvb) * 64), hh_ = ATT_VTR(vb_ + ((ms) * 16 + 8) * 320 + (dvb) * 64); \
;         const bf16x8 vf_ = (bf16x8){lo_[0], lo_[1], lo_[2], lo_[3], hh_[0], hh_[1], hh_[2], hh_[3]}; \
;         o[dvb] = ATT_MFMA(vf_, __builtin_bit_cast(bf16x8, pw##ms), o[dvb]); } while (0)
; __device__ __forceinline__ void attn_unit(LAS unsigned char* lds, const bf16_t* PROJ, bf16_t* OCAT, const float* subg, float lam, float oml, int b, int h, int qb) {
;     ...
;     {
;         float sacc = 0.f;
; #pragma unroll
;         for (int r = 0; r < 16; ++r) sacc += pB0[r] + pB1[r];
;         lrun += sacc;
;         u32x4 pw0, pw1, pw2, pw3;
;         pw0.x = cvtpk_s(pB0[0], pB0[1]); pw0.y = cvtpk_s(pB0[2], pB0[3]); pw0.z = cvtpk_s(pB0[4], pB0[5]); pw0.w = cvtpk_s(pB0[6], pB0[7]);
;         pw1.x = cvtpk_s(pB0[8], pB0[9]); pw1.y = cvtpk_s(pB0[10], pB0[11]); pw1.z = cvtpk_s(pB0[12], pB0[13]); pw1.w = cvtpk_s(pB0[14], pB0[15]);
;         pw2.x = cvtpk_s(pB1[0], pB1[1]); pw2.y = cvtpk_s(pB1[2], pB1[3]); pw2.z = cvtpk_s(pB1[4], pB1[5]); pw2.w = cvtpk_s(pB1[6], pB1[7]);
;         pw3.x = cvtpk_s(pB1[8], pB1[9]); pw3.y = cvtpk_s(pB1[10], pB1[11]); pw3.z = cvtpk_s(pB1[12], pB1[13]); pw3.w = cvtpk_s(pB1[14], pB1[15]);
;         const LAS unsigned char* vb_ = lds + vs_prev + vread;
;     ...
;         ATT_GD(0, 0); ATT_GD(0, 1); ATT_GD(0, 2); ATT_GD(0, 3); ATT_GD(1, 0); ATT_GD(1, 1); ATT_GD(1, 2); ATT_GD(1, 3);
;         ATT_GD(2, 0); ATT_GD(2, 1); ATT_GD(2, 2); ATT_GD(2, 3); ATT_GD(3, 0); ATT_GD(3, 1); ATT_GD(3, 2); ATT_GD(3, 3);
;     ...
;     }
;     __syncthreads();
.LBB0_455:
	v_add_f32_e32 v80, v112, v64
	v_add_f32_e32 v80, 0, v80
	v_add_f32_e32 v81, v113, v65
	v_add_f32_e32 v80, v81, v80
	v_add_f32_e32 v81, v114, v66
	v_add_f32_e32 v80, v81, v80
	v_add_f32_e32 v81, v115, v67
	v_add_f32_e32 v80, v81, v80
	v_add_f32_e32 v81, v116, v68
	v_add_f32_e32 v80, v81, v80
	v_add_f32_e32 v81, v117, v69
	v_add_f32_e32 v80, v81, v80
	v_add_f32_e32 v81, v118, v70
	v_add_f32_e32 v80, v81, v80
	v_add_f32_e32 v81, v119, v71
	v_add_f32_e32 v80, v81, v80
	v_add_f32_e32 v81, v120, v72
	v_add_f32_e32 v80, v81, v80
	v_add_f32_e32 v81, v121, v73
	v_add_f32_e32 v80, v81, v80
	v_add_f32_e32 v81, v122, v74
	v_add_f32_e32 v80, v81, v80
	v_add_f32_e32 v81, v123, v75
	v_add_f32_e32 v82, v81, v80
	v_pk_add_f32 v[80:81], v[124:125], v[76:77]
	v_cvt_pk_bf16_f32 v83, v70, v71
	v_add_f32_e32 v80, v80, v82
	v_add_f32_e32 v82, v81, v80
	v_pk_add_f32 v[80:81], v[126:127], v[78:79]
	v_cvt_pk_bf16_f32 v90, v112, v113
	v_add_f32_e32 v80, v80, v82
	v_add_f32_e32 v80, v81, v80
	v_add_f32_e32 v88, v145, v80
	v_cvt_pk_bf16_f32 v80, v64, v65
	v_cvt_pk_bf16_f32 v64, v72, v73
	ds_read_b64_tr_b16 v[70:71], v160 offset:61440
	ds_read_b64_tr_b16 v[72:73], v160 offset:64000
	v_cvt_pk_bf16_f32 v91, v114, v115
	v_cvt_pk_bf16_f32 v92, v116, v117
	v_cvt_pk_bf16_f32 v93, v118, v119
	v_cvt_pk_bf16_f32 v82, v68, v69
	v_add_u32_e32 v68, 0xf000, v160
	s_waitcnt lgkmcnt(0)
	v_mfma_f32_32x32x16_bf16 v[0:15], v[70:73], v[90:93], v[0:15]
	ds_read_b64_tr_b16 v[70:71], v160 offset:61504
	ds_read_b64_tr_b16 v[72:73], v160 offset:64064
	v_cvt_pk_bf16_f32 v84, v120, v121
	v_cvt_pk_bf16_f32 v85, v122, v123
	v_cvt_pk_bf16_f32 v86, v124, v125
	v_cvt_pk_bf16_f32 v87, v126, v127
	v_cvt_pk_bf16_f32 v81, v66, v67
	v_cvt_pk_bf16_f32 v65, v74, v75
	s_waitcnt lgkmcnt(0)
	v_mfma_f32_32x32x16_bf16 v[48:63], v[70:73], v[90:93], v[48:63]
	ds_read_b64_tr_b16 v[70:71], v160 offset:61568
	ds_read_b64_tr_b16 v[72:73], v160 offset:64128
	v_cvt_pk_bf16_f32 v66, v76, v77
	v_cvt_pk_bf16_f32 v67, v78, v79
	s_lshl_b32 s70, s69, 1
	s_add_u32 s16, s48, s70
	s_addc_u32 s17, s49, 0
	s_cmp_eq_u32 s84, 1
	s_waitcnt lgkmcnt(0)
	v_mfma_f32_32x32x16_bf16 v[32:47], v[70:73], v[90:93], v[32:47]
	ds_read_b64_tr_b16 v[70:71], v160 offset:61632
	ds_read_b64_tr_b16 v[72:73], v160 offset:64192
	s_mul_i32 s84, s84, 0x10800
	s_cselect_b64 s[4:5], -1, 0
	s_add_i32 s18, s84, 0
	s_add_i32 s65, s65, s34
	s_add_i32 s64, s64, s34
	s_cmpk_gt_i32 s65, 0x3ff
	s_waitcnt lgkmcnt(0)
	v_mfma_f32_32x32x16_bf16 v[16:31], v[70:73], v[90:93], v[16:31]
	ds_read_b64_tr_b16 v[70:71], v68 offset:5120
	ds_read_b64_tr_b16 v[72:73], v68 offset:7680
	s_waitcnt lgkmcnt(0)
	v_mfma_f32_32x32x16_bf16 v[0:15], v[70:73], v[84:87], v[0:15]
	ds_read_b64_tr_b16 v[70:71], v68 offset:5184
	ds_read_b64_tr_b16 v[72:73], v68 offset:7744
	s_waitcnt lgkmcnt(0)
	v_mfma_f32_32x32x16_bf16 v[48:63], v[70:73], v[84:87], v[48:63]
	ds_read_b64_tr_b16 v[70:71], v68 offset:5248
	ds_read_b64_tr_b16 v[72:73], v68 offset:7808
	s_waitcnt lgkmcnt(0)
	v_mfma_f32_32x32x16_bf16 v[32:47], v[70:73], v[84:87], v[32:47]
	ds_read_b64_tr_b16 v[70:71], v68 offset:5312
	ds_read_b64_tr_b16 v[72:73], v68 offset:7872
	s_waitcnt lgkmcnt(0)
	v_mfma_f32_32x32x16_bf16 v[16:31], v[70:73], v[84:87], v[16:31]
	ds_read_b64_tr_b16 v[70:71], v68 offset:10240
	ds_read_b64_tr_b16 v[72:73], v68 offset:12800
	s_waitcnt lgkmcnt(0)
	v_mfma_f32_32x32x16_bf16 v[0:15], v[70:73], v[80:83], v[0:15]
	ds_read_b64_tr_b16 v[70:71], v68 offset:10304
	ds_read_b64_tr_b16 v[72:73], v68 offset:12864
	s_waitcnt lgkmcnt(0)
	v_mfma_f32_32x32x16_bf16 v[48:63], v[70:73], v[80:83], v[48:63]
	ds_read_b64_tr_b16 v[70:71], v68 offset:10368
	ds_read_b64_tr_b16 v[72:73], v68 offset:12928
	s_waitcnt lgkmcnt(0)
	v_mfma_f32_32x32x16_bf16 v[32:47], v[70:73], v[80:83], v[32:47]
	ds_read_b64_tr_b16 v[70:71], v68 offset:10432
	ds_read_b64_tr_b16 v[72:73], v68 offset:12992
	s_waitcnt lgkmcnt(0)
	v_mfma_f32_32x32x16_bf16 v[16:31], v[70:73], v[80:83], v[16:31]
	ds_read_b64_tr_b16 v[70:71], v68 offset:15360
	ds_read_b64_tr_b16 v[72:73], v68 offset:17920
	s_waitcnt lgkmcnt(0)
	v_mfma_f32_32x32x16_bf16 v[0:15], v[70:73], v[64:67], v[0:15]
	ds_read_b64_tr_b16 v[70:71], v68 offset:15424
	ds_read_b64_tr_b16 v[72:73], v68 offset:17984
	s_waitcnt lgkmcnt(0)
	v_mfma_f32_32x32x16_bf16 v[48:63], v[70:73], v[64:67], v[48:63]
	ds_read_b64_tr_b16 v[70:71], v68 offset:15488
	ds_read_b64_tr_b16 v[72:73], v68 offset:18048
	s_waitcnt lgkmcnt(0)
	v_mfma_f32_32x32x16_bf16 v[32:47], v[70:73], v[64:67], v[32:47]
	ds_read_b64_tr_b16 v[70:71], v68 offset:15552
	ds_read_b64_tr_b16 v[72:73], v68 offset:18112
	s_waitcnt lgkmcnt(0)
	s_barrier
; #define LAS __attribute__((address_space(3)))
; __device__ __forceinline__ float half_sum(float m) { auto rr = __builtin_amdgcn_permlane32_swap(__float_as_uint(m), __float_as_uint(m), false, false); return __uint_as_float(rr[0]) + __uint_as_float(rr[1]); }
; __device__ __forceinline__ void attn_unit(LAS unsigned char* lds, const bf16_t* PROJ, bf16_t* OCAT, const float* subg, float lam, float oml, int b, int h, int qb) {
;     ...
;         const float ltot = half_sum(lrun);
;         float inv = 1.0f / ltot; if (comp == 1) inv *= lam;
;         LAS float* cb = (LAS float*)lds + comp * (128 * 132) + (wq * 32 + r32) * 132 + 4 * hi;
; #pragma unroll
;         for (int dvb = 0; dvb < 4; ++dvb)
; #pragma unroll
;             for (int k4 = 0; k4 < 4; ++k4) {
;                 const f32x4 v = (f32x4){o[dvb][4 * k4 + 0] * inv, o[dvb][4 * k4 + 1] * inv, o[dvb][4 * k4 + 2] * inv, o[dvb][4 * k4 + 3] * inv};
;                 *(LAS f32x4*)(cb + dvb * 32 + 8 * k4) = v;
;             }
;     }
;     __syncthreads();
;     {
;         const int q2 = tid >> 2, part = tid & 3;
;         const LAS float* a0 = (const LAS float*)lds + q2 * 132 + part * 32; const LAS float* a1 = a0 + 128 * 132;
;         f32x4 a[8]; float ss = 0.f;
; #pragma unroll
;         for (int i = 0; i < 8; ++i) { a[i] = *(const LAS f32x4*)(a0 + 4 * i) - *(const LAS f32x4*)(a1 + 4 * i); ss += (a[i].x * a[i].x + a[i].y * a[i].y) + (a[i].z * a[i].z + a[i].w * a[i].w); }
;         ss += __shfl_xor(ss, 1); ss += __shfl_xor(ss, 2);
	v_mfma_f32_32x32x16_bf16 v[16:31], v[70:73], v[64:67], v[16:31]
	v_mul_u32_u24_e32 v64, 0x210, v240
	v_lshlrev_b32_e32 v65, 2, v224
	v_lshlrev_b32_e32 v66, 5, v239
	v_add3_u32 v71, s18, v64, v65
	v_ashrrev_i32_e32 v64, 2, v239
	s_movk_i32 s18, 0x210
	v_and_b32_e32 v74, 0x60, v66
	v_mul_lo_u32 v65, v64, s18
	v_lshlrev_b32_e32 v68, 2, v74
	v_and_b32_e32 v66, 64, v235
	v_add3_u32 v70, 0, v65, v68
	v_xor_b32_e32 v65, 1, v235
	v_add_u32_e32 v66, 64, v66
	v_cmp_lt_i32_e32 vcc, v65, v66
	v_lshlrev_b32_e32 v224, 1, v74
	s_nop 0
	v_cndmask_b32_e32 v75, v235, v65, vcc
	v_xor_b32_e32 v65, 2, v235
	v_cmp_lt_i32_e32 vcc, v65, v66
	v_mov_b64_e32 v[66:67], s[6:7]
	s_nop 0
	v_cndmask_b32_e32 v69, v235, v65, vcc
	v_ashrrev_i32_e32 v65, 31, v64
	v_lshl_add_u64 v[64:65], s[82:83], 0, v[64:65]
	v_mad_u64_u32 v[66:67], s[18:19], v64, s52, v[66:67]
	v_mov_b32_e32 v72, v67
	v_mad_u64_u32 v[72:73], s[18:19], v65, s52, v[72:73]
	v_mov_b32_e32 v67, v72
	v_mov_b32_e32 v72, v88
	s_nop 1
	v_permlane32_swap_b32_e32 v88, v72
	v_lshlrev_b64 v[64:65], 12, v[64:65]
	v_add_f32_e32 v72, v88, v72
	v_lshl_add_u64 v[64:65], s[16:17], 0, v[64:65]
	v_lshl_add_u64 v[64:65], v[64:65], 0, v[224:225]
	v_rcp_f32_e32 v72, v72
	s_nop 0
	v_mul_f32_e32 v73, v237, v72
	v_cndmask_b32_e64 v72, v72, v73, s[4:5]
	v_pk_mul_f32 v[0:1], v[0:1], v[72:73] op_sel_hi:[1,0]
	v_pk_mul_f32 v[2:3], v[2:3], v[72:73] op_sel_hi:[1,0]
	ds_write_b128 v71, v[0:3]
	v_pk_mul_f32 v[0:1], v[4:5], v[72:73] op_sel_hi:[1,0]
	v_pk_mul_f32 v[2:3], v[6:7], v[72:73] op_sel_hi:[1,0]
	ds_write_b128 v71, v[0:3] offset:32
	v_pk_mul_f32 v[0:1], v[8:9], v[72:73] op_sel_hi:[1,0]
	v_pk_mul_f32 v[2:3], v[10:11], v[72:73] op_sel_hi:[1,0]
	ds_write_b128 v71, v[0:3] offset:64
	v_pk_mul_f32 v[0:1], v[12:13], v[72:73] op_sel_hi:[1,0]
	v_pk_mul_f32 v[2:3], v[14:15], v[72:73] op_sel_hi:[1,0]
	ds_write_b128 v71, v[0:3] offset:96
	v_pk_mul_f32 v[0:1], v[48:49], v[72:73] op_sel_hi:[1,0]
	v_pk_mul_f32 v[2:3], v[50:51], v[72:73] op_sel_hi:[1,0]
	ds_write_b128 v71, v[0:3] offset:128
	v_pk_mul_f32 v[0:1], v[52:53], v[72:73] op_sel_hi:[1,0]
	v_pk_mul_f32 v[2:3], v[54:55], v[72:73] op_sel_hi:[1,0]
	ds_write_b128 v71, v[0:3] offset:160
	v_pk_mul_f32 v[0:1], v[56:57], v[72:73] op_sel_hi:[1,0]
	v_pk_mul_f32 v[2:3], v[58:59], v[72:73] op_sel_hi:[1,0]
	ds_write_b128 v71, v[0:3] offset:192
	v_pk_mul_f32 v[0:1], v[60:61], v[72:73] op_sel_hi:[1,0]
	v_pk_mul_f32 v[2:3], v[62:63], v[72:73] op_sel_hi:[1,0]
	ds_write_b128 v71, v[0:3] offset:224
	v_pk_mul_f32 v[0:1], v[32:33], v[72:73] op_sel_hi:[1,0]
	v_pk_mul_f32 v[2:3], v[34:35], v[72:73] op_sel_hi:[1,0]
	ds_write_b128 v71, v[0:3] offset:256
	v_pk_mul_f32 v[0:1], v[36:37], v[72:73] op_sel_hi:[1,0]
	v_pk_mul_f32 v[2:3], v[38:39], v[72:73] op_sel_hi:[1,0]
	ds_write_b128 v71, v[0:3] offset:288
	v_pk_mul_f32 v[0:1], v[40:41], v[72:73] op_sel_hi:[1,0]
	v_pk_mul_f32 v[2:3], v[42:43], v[72:73] op_sel_hi:[1,0]
	ds_write_b128 v71, v[0:3] offset:320
	v_pk_mul_f32 v[0:1], v[44:45], v[72:73] op_sel_hi:[1,0]
	v_pk_mul_f32 v[2:3], v[46:47], v[72:73] op_sel_hi:[1,0]
	ds_write_b128 v71, v[0:3] offset:352
	v_pk_mul_f32 v[0:1], v[16:17], v[72:73] op_sel_hi:[1,0]
	v_pk_mul_f32 v[2:3], v[18:19], v[72:73] op_sel_hi:[1,0]
	ds_write_b128 v71, v[0:3] offset:384
	v_pk_mul_f32 v[0:1], v[20:21], v[72:73] op_sel_hi:[1,0]
	v_pk_mul_f32 v[2:3], v[22:23], v[72:73] op_sel_hi:[1,0]
	ds_write_b128 v71, v[0:3] offset:416
	v_pk_mul_f32 v[0:1], v[24:25], v[72:73] op_sel_hi:[1,0]
	v_pk_mul_f32 v[2:3], v[26:27], v[72:73] op_sel_hi:[1,0]
	ds_write_b128 v71, v[0:3] offset:448
	v_pk_mul_f32 v[0:1], v[28:29], v[72:73] op_sel_hi:[1,0]
	v_pk_mul_f32 v[2:3], v[30:31], v[72:73] op_sel_hi:[1,0]
	ds_write_b128 v71, v[0:3] offset:480
	v_add_u32_e32 v10, 0x10800, v70
	s_waitcnt lgkmcnt(0)
	s_barrier
	ds_read_b128 v[2:5], v70
	ds_read_b128 v[6:9], v70 offset:16
	ds_read_b128 v[14:17], v70 offset:32
	ds_read_b128 v[18:21], v70 offset:48
	ds_read_b128 v[22:25], v10
	v_lshlrev_b32_e32 v48, 2, v75
	v_lshl_add_u64 v[0:1], v[66:67], 0, s[70:71]
	v_lshl_add_u64 v[0:1], v[0:1], 0, v[224:225]
	s_mov_b64 s[4:5], 0x1800
	s_waitcnt lgkmcnt(0)
	v_sub_f32_e32 v42, v2, v22
	v_add_u32_e32 v2, 0x10810, v70
	v_sub_f32_e32 v41, v5, v25
	v_sub_f32_e32 v40, v4, v24
	v_sub_f32_e32 v43, v3, v23
	ds_read_b128 v[2:5], v2
	v_lshl_add_u64 v[12:13], v[0:1], 0, s[4:5]
	global_load_dwordx4 v[180:183], v68, s[8:9]
	global_load_dwordx4 v[184:187], v68, s[8:9] offset:16
	global_load_dwordx4 v[188:191], v68, s[8:9] offset:32
	global_load_dwordx4 v[192:195], v68, s[8:9] offset:48
	global_load_dwordx4 v[196:199], v68, s[8:9] offset:64
	global_load_dwordx4 v[200:203], v68, s[8:9] offset:80
	global_load_dwordx4 v[204:207], v68, s[8:9] offset:96
	global_load_dwordx4 v[208:211], v68, s[8:9] offset:112
	s_movk_i32 s4, 0x1000
	s_waitcnt lgkmcnt(0)
	v_sub_f32_e32 v47, v7, v3
	v_sub_f32_e32 v45, v9, v5
	v_sub_f32_e32 v44, v8, v4
	v_sub_f32_e32 v46, v6, v2
	v_mov_b32_e32 v4, v43
	v_mov_b32_e32 v5, v47
	v_mov_b32_e32 v2, v42
	v_mov_b32_e32 v3, v46
	v_pk_mul_f32 v[4:5], v[4:5], v[4:5]
	v_mov_b32_e32 v6, v41
	v_mov_b32_e32 v7, v45
	v_pk_fma_f32 v[2:3], v[2:3], v[2:3], v[4:5]
	v_mov_b32_e32 v4, v40
	v_mov_b32_e32 v5, v44
	v_pk_mul_f32 v[6:7], v[6:7], v[6:7]
	s_nop 0
	v_pk_fma_f32 v[4:5], v[4:5], v[4:5], v[6:7]
	s_nop 0
	v_pk_add_f32 v[10:11], v[2:3], v[4:5]
	v_add_u32_e32 v2, 0x10820, v70
	ds_read_b128 v[2:5], v2
	s_waitcnt lgkmcnt(0)
	v_sub_f32_e32 v33, v15, v3
	v_sub_f32_e32 v32, v14, v2
	v_sub_f32_e32 v35, v17, v5
	v_sub_f32_e32 v34, v16, v4
	v_pk_mul_f32 v[2:3], v[34:35], v[34:35]
	v_pk_mul_f32 v[4:5], v[32:33], v[32:33]
	s_nop 0
	v_pk_mov_b32 v[6:7], v[4:5], v[2:3] op_sel:[1,0]
	v_mov_b32_e32 v5, v3
	v_add_u32_e32 v2, 0x10830, v70
	v_pk_add_f32 v[14:15], v[6:7], v[4:5]
	ds_read_b128 v[2:5], v2
	v_add_u32_e32 v6, 0x10840, v70
	ds_read_b128 v[6:9], v6
	s_waitcnt lgkmcnt(1)
; __device__ __forceinline__ unsigned cvt_pk_bf16(float lo, float hi) { unsigned r; asm volatile("v_cvt_pk_bf16_f32 %0, %1, %2" : "=v"(r) : "v"(lo), "v"(hi)); return r; }
; __device__ __forceinline__ float bflo(unsigned w) { return __uint_as_float(w << 16); }
; __device__ __forceinline__ float bfhi(unsigned w) { return __uint_as_float(w & 0xffff0000u); }
; __device__ __forceinline__ float silu_f(float z) { return z / (1.0f + __expf(-z)); }
; __device__ __forceinline__ void attn_unit(LAS unsigned char* lds, const bf16_t* PROJ, bf16_t* OCAT, const float* subg, float lam, float oml, int b, int h, int qb) {
;     ...
;         const float rs = rsqrtf(ss * (1.0f / 128.0f) + EPS) * oml;
;         const size_t row = rowbase + q0 + q2;
;         const bf16_t* zp = PROJ + row * PP + C_ZA + h * 128 + part * 32; bf16_t* op = OCAT + row * 2048 + h * 128 + part * 32; const float* gp = subg + part * 32;
; #pragma unroll
;         for (int i = 0; i < 4; ++i) {
;             const u32x4 z = *(const u32x4*)(zp + 8 * i); const f32x4 ga = *(const f32x4*)(gp + 8 * i), gb = *(const f32x4*)(gp + 8 * i + 4);
;             const f32x4 xa = a[2 * i] * rs * ga, xb = a[2 * i + 1] * rs * gb;
;             u32x4 w; w.x = cvt_pk_bf16(xa.x * silu_f(bflo(z.x)), xa.y * silu_f(bfhi(z.x))); w.y = cvt_pk_bf16(xa.z * silu_f(bflo(z.y)), xa.w * silu_f(bfhi(z.y)));
;             w.z = cvt_pk_bf16(xb.x * silu_f(bflo(z.z)), xb.y * silu_f(bfhi(z.z))); w.w = cvt_pk_bf16(xb.z * silu_f(bflo(z.w)), xb.w * silu_f(bfhi(z.w)));
;             *(u32x4*)(op + 8 * i) = w;
	v_sub_f32_e32 v37, v19, v3
	v_sub_f32_e32 v36, v18, v2
	v_sub_f32_e32 v39, v21, v5
	v_sub_f32_e32 v38, v20, v4
	ds_read_b128 v[2:5], v70 offset:64
	s_waitcnt lgkmcnt(0)
	v_sub_f32_e32 v26, v2, v6
	v_sub_f32_e32 v24, v4, v8
	v_sub_f32_e32 v27, v3, v7
	v_mul_f32_e32 v4, v26, v26
	v_pk_add_f32 v[2:3], v[10:11], v[10:11] op_sel:[0,1] op_sel_hi:[1,0]
	v_sub_f32_e32 v25, v5, v9
	v_mul_f32_e32 v6, v27, v27
	v_mov_b32_e32 v3, v4
	v_pk_add_f32 v[4:5], v[14:15], v[14:15] op_sel:[0,1] op_sel_hi:[1,0]
	v_mul_f32_e32 v7, v24, v24
	v_mov_b32_e32 v5, v6
	v_pk_add_f32 v[2:3], v[2:3], v[4:5]
	v_mul_f32_e32 v4, v37, v37
	v_pk_fma_f32 v[4:5], v[36:37], v[36:37], v[4:5] op_sel_hi:[1,1,0]
	v_mul_f32_e32 v6, v39, v39
	v_mul_f32_e32 v8, v25, v25
	v_mov_b32_e32 v5, v7
	v_pk_fma_f32 v[6:7], v[38:39], v[38:39], v[6:7] op_sel_hi:[1,1,0]
	s_nop 0
	v_mov_b32_e32 v7, v8
	v_pk_add_f32 v[4:5], v[4:5], v[6:7]
	v_add_u32_e32 v6, 0x10850, v70
	v_pk_add_f32 v[10:11], v[2:3], v[4:5]
	ds_read_b128 v[2:5], v70 offset:80
	ds_read_b128 v[6:9], v6
	s_waitcnt lgkmcnt(0)
	v_sub_f32_e32 v29, v3, v7
	v_sub_f32_e32 v28, v2, v6
	v_sub_f32_e32 v31, v5, v9
	v_sub_f32_e32 v30, v4, v8
	v_pk_mul_f32 v[2:3], v[30:31], v[30:31]
	v_pk_mul_f32 v[4:5], v[28:29], v[28:29]
	s_nop 0
	v_pk_mov_b32 v[6:7], v[4:5], v[2:3] op_sel:[1,0]
	v_mov_b32_e32 v5, v3
	v_pk_add_f32 v[22:23], v[6:7], v[4:5]
	v_add_u32_e32 v6, 0x10860, v70
	ds_read_b128 v[2:5], v70 offset:96
	ds_read_b128 v[6:9], v6
	s_waitcnt lgkmcnt(0)
	v_sub_f32_e32 v14, v2, v6
	v_add_u32_e32 v6, 0x10870, v70
	v_sub_f32_e32 v15, v3, v7
	v_sub_f32_e32 v17, v5, v9
	v_sub_f32_e32 v16, v4, v8
	ds_read_b128 v[2:5], v70 offset:112
	ds_read_b128 v[6:9], v6
	s_waitcnt lgkmcnt(0)
	v_sub_f32_e32 v20, v2, v6
	v_sub_f32_e32 v18, v4, v8
	v_sub_f32_e32 v21, v3, v7
	v_mul_f32_e32 v4, v20, v20
	v_pk_add_f32 v[2:3], v[10:11], v[10:11] op_sel:[0,1] op_sel_hi:[1,0]
	v_sub_f32_e32 v19, v5, v9
	v_mul_f32_e32 v6, v21, v21
	v_mov_b32_e32 v3, v4
	v_pk_add_f32 v[4:5], v[22:23], v[22:23] op_sel:[0,1] op_sel_hi:[1,0]
	v_mul_f32_e32 v7, v18, v18
	v_mov_b32_e32 v5, v6
	v_pk_add_f32 v[2:3], v[2:3], v[4:5]
	v_mul_f32_e32 v4, v15, v15
	v_pk_fma_f32 v[4:5], v[14:15], v[14:15], v[4:5] op_sel_hi:[1,1,0]
	v_mul_f32_e32 v6, v17, v17
	v_mul_f32_e32 v8, v19, v19
	v_mov_b32_e32 v5, v7
	v_pk_fma_f32 v[6:7], v[16:17], v[16:17], v[6:7] op_sel_hi:[1,1,0]
	s_nop 0
	v_mov_b32_e32 v7, v8
	v_pk_add_f32 v[4:5], v[4:5], v[6:7]
	s_nop 0
	v_pk_add_f32 v[2:3], v[2:3], v[4:5]
	s_nop 0
	v_add_f32_e32 v2, v2, v3
	ds_bpermute_b32 v4, v48, v2
	v_lshlrev_b32_e32 v3, 2, v69
	s_waitcnt lgkmcnt(0)
	v_add_f32_e32 v2, v2, v4
	ds_bpermute_b32 v3, v3, v2
	s_waitcnt lgkmcnt(0)
	v_add_f32_e32 v2, v2, v3
	v_mov_b32_e32 v3, 0x358637bd
	v_fmamk_f32 v2, v2, 0x3c000000, v3
	v_cmp_gt_f32_e32 vcc, s62, v2
	v_mul_f32_e32 v3, 0x4b800000, v2
	s_nop 0
	v_cndmask_b32_e32 v2, v2, v3, vcc
	v_rsq_f32_e32 v2, v2
	s_nop 0
	v_mul_f32_e32 v3, 0x45800000, v2
	v_cndmask_b32_e32 v2, v2, v3, vcc
	v_add_co_u32_e32 v0, vcc, s4, v0
	v_mul_f32_e32 v22, v238, v2
	s_nop 0
	v_addc_co_u32_e32 v1, vcc, 0, v1, vcc
	v_pk_mul_f32 v[42:43], v[42:43], v[22:23] op_sel_hi:[1,0]
	v_pk_mul_f32 v[40:41], v[40:41], v[22:23] op_sel_hi:[1,0]
	s_waitcnt vmcnt(0)
	v_mov_b64_e32 v[0:1], v[164:165]
	v_mov_b64_e32 v[2:3], v[166:167]
	v_mov_b64_e32 v[4:5], v[184:185]
	v_mov_b64_e32 v[6:7], v[186:187]
	v_mov_b64_e32 v[8:9], v[180:181]
	v_mov_b64_e32 v[10:11], v[182:183]
	v_pk_mul_f32 v[8:9], v[8:9], v[42:43]
	v_pk_mul_f32 v[10:11], v[10:11], v[40:41]
	v_pk_mul_f32 v[40:41], v[46:47], v[22:23] op_sel_hi:[1,0]
	v_pk_mul_f32 v[42:43], v[44:45], v[22:23] op_sel_hi:[1,0]
	v_lshlrev_b32_e32 v23, 16, v0
	v_pk_mul_f32 v[4:5], v[4:5], v[40:41]
	v_mul_f32_e32 v40, 0xbfb8aa3b, v23
	v_exp_f32_e32 v40, v40
	v_pk_mul_f32 v[6:7], v[6:7], v[42:43]
	v_and_b32_e32 v0, 0xffff0000, v0
	v_add_f32_e32 v40, 1.0, v40
	v_rcp_f32_e32 v41, v40
	s_nop 0
	v_mul_f32_e32 v23, v23, v41
	v_mul_f32_e32 v8, v23, v8
	v_mul_f32_e32 v23, 0xbfb8aa3b, v0
	v_exp_f32_e32 v23, v23
	s_nop 0
	v_add_f32_e32 v23, 1.0, v23
	v_rcp_f32_e32 v40, v23
	s_nop 0
	v_mul_f32_e32 v0, v0, v40
	v_mul_f32_e32 v0, v0, v9
	v_cvt_pk_bf16_f32 v0, v8, v0
	v_lshlrev_b32_e32 v8, 16, v1
	v_mul_f32_e32 v9, 0xbfb8aa3b, v8
	v_exp_f32_e32 v9, v9
	v_and_b32_e32 v1, 0xffff0000, v1
	v_add_f32_e32 v9, 1.0, v9
	v_rcp_f32_e32 v23, v9
	s_nop 0
	v_mul_f32_e32 v8, v8, v23
	v_mul_f32_e32 v9, 0xbfb8aa3b, v1
	v_exp_f32_e32 v9, v9
	v_mul_f32_e32 v8, v8, v10
	v_add_f32_e32 v9, 1.0, v9
	v_rcp_f32_e32 v10, v9
	s_nop 0
	v_mul_f32_e32 v1, v1, v10
	v_mul_f32_e32 v1, v1, v11
	v_cvt_pk_bf16_f32 v1, v8, v1
	v_lshlrev_b32_e32 v8, 16, v2
	v_mul_f32_e32 v9, 0xbfb8aa3b, v8
	v_exp_f32_e32 v9, v9
	v_and_b32_e32 v2, 0xffff0000, v2
	v_add_f32_e32 v9, 1.0, v9
	v_rcp_f32_e32 v10, v9
	s_nop 0
	v_mul_f32_e32 v8, v8, v10
	v_mul_f32_e32 v4, v8, v4
	v_mul_f32_e32 v8, 0xbfb8aa3b, v2
	v_exp_f32_e32 v8, v8
	s_nop 0
	v_add_f32_e32 v8, 1.0, v8
	v_rcp_f32_e32 v9, v8
	s_nop 0
	v_mul_f32_e32 v2, v2, v9
	v_mul_f32_e32 v2, v2, v5
	v_cvt_pk_bf16_f32 v2, v4, v2
	v_lshlrev_b32_e32 v4, 16, v3
	v_mul_f32_e32 v5, 0xbfb8aa3b, v4
	v_exp_f32_e32 v5, v5
	v_and_b32_e32 v3, 0xffff0000, v3
	v_add_f32_e32 v5, 1.0, v5
	v_rcp_f32_e32 v8, v5
	s_nop 0
	v_mul_f32_e32 v4, v4, v8
	v_mul_f32_e32 v5, 0xbfb8aa3b, v3
	v_exp_f32_e32 v5, v5
	v_mul_f32_e32 v4, v4, v6
	v_add_f32_e32 v5, 1.0, v5
	v_rcp_f32_e32 v6, v5
	s_nop 0
	v_mul_f32_e32 v3, v3, v6
	v_mul_f32_e32 v3, v3, v7
	v_cvt_pk_bf16_f32 v3, v4, v3
	global_store_dwordx4 v[64:65], v[0:3], off
	v_pk_mul_f32 v[10:11], v[32:33], v[22:23] op_sel_hi:[1,0]
	v_pk_mul_f32 v[8:9], v[34:35], v[22:23] op_sel_hi:[1,0]
	s_nop 0
	v_mov_b64_e32 v[0:1], v[168:169]
; __device__ __forceinline__ unsigned cvt_pk_bf16(float lo, float hi) { unsigned r; asm volatile("v_cvt_pk_bf16_f32 %0, %1, %2" : "=v"(r) : "v"(lo), "v"(hi)); return r; }
; __device__ __forceinline__ float bflo(unsigned w) { return __uint_as_float(w << 16); }
; __device__ __forceinline__ float bfhi(unsigned w) { return __uint_as_float(w & 0xffff0000u); }
; __device__ __forceinline__ float silu_f(float z) { return z / (1.0f + __expf(-z)); }
; __device__ __forceinline__ void attn_unit(LAS unsigned char* lds, const bf16_t* PROJ, bf16_t* OCAT, const float* subg, float lam, float oml, int b, int h, int qb) {
;     ...
;         for (int i = 0; i < 4; ++i) {
;             const u32x4 z = *(const u32x4*)(zp + 8 * i); const f32x4 ga = *(const f32x4*)(gp + 8 * i), gb = *(const f32x4*)(gp + 8 * i + 4);
;             const f32x4 xa = a[2 * i] * rs * ga, xb = a[2 * i + 1] * rs * gb;
;             u32x4 w; w.x = cvt_pk_bf16(xa.x * silu_f(bflo(z.x)), xa.y * silu_f(bfhi(z.x))); w.y = cvt_pk_bf16(xa.z * silu_f(bflo(z.y)), xa.w * silu_f(bfhi(z.y)));
;             w.z = cvt_pk_bf16(xb.x * silu_f(bflo(z.z)), xb.y * silu_f(bfhi(z.z))); w.w = cvt_pk_bf16(xb.z * silu_f(bflo(z.w)), xb.w * silu_f(bfhi(z.w)));
;             *(u32x4*)(op + 8 * i) = w;
	v_mov_b64_e32 v[2:3], v[170:171]
	v_mov_b64_e32 v[40:41], v[192:193]
	v_mov_b64_e32 v[42:43], v[194:195]
	v_mov_b64_e32 v[4:5], v[188:189]
	v_mov_b64_e32 v[6:7], v[190:191]
	v_pk_mul_f32 v[10:11], v[4:5], v[10:11]
	v_pk_mul_f32 v[8:9], v[6:7], v[8:9]
	v_pk_mul_f32 v[6:7], v[36:37], v[22:23] op_sel_hi:[1,0]
	v_pk_mul_f32 v[4:5], v[38:39], v[22:23] op_sel_hi:[1,0]
	v_lshlrev_b32_e32 v23, 16, v0
	v_mul_f32_e32 v32, 0xbfb8aa3b, v23
	v_exp_f32_e32 v32, v32
	v_and_b32_e32 v0, 0xffff0000, v0
	v_pk_mul_f32 v[6:7], v[40:41], v[6:7]
	v_pk_mul_f32 v[4:5], v[42:43], v[4:5]
	v_add_f32_e32 v32, 1.0, v32
	v_rcp_f32_e32 v33, v32
	s_nop 0
	v_mul_f32_e32 v23, v23, v33
	v_mul_f32_e32 v10, v23, v10
	v_mul_f32_e32 v23, 0xbfb8aa3b, v0
	v_exp_f32_e32 v23, v23
	s_nop 0
	v_add_f32_e32 v23, 1.0, v23
	v_rcp_f32_e32 v32, v23
	s_nop 0
	v_mul_f32_e32 v0, v0, v32
	v_mul_f32_e32 v0, v0, v11
	v_cvt_pk_bf16_f32 v0, v10, v0
	v_lshlrev_b32_e32 v10, 16, v1
	v_mul_f32_e32 v11, 0xbfb8aa3b, v10
	v_exp_f32_e32 v11, v11
	v_and_b32_e32 v1, 0xffff0000, v1
	v_add_f32_e32 v11, 1.0, v11
	v_rcp_f32_e32 v23, v11
	s_nop 0
	v_mul_f32_e32 v10, v10, v23
	v_mul_f32_e32 v8, v10, v8
	v_mul_f32_e32 v10, 0xbfb8aa3b, v1
	v_exp_f32_e32 v10, v10
	s_nop 0
	v_add_f32_e32 v10, 1.0, v10
	v_rcp_f32_e32 v11, v10
	s_nop 0
	v_mul_f32_e32 v1, v1, v11
	v_mul_f32_e32 v1, v1, v9
	v_cvt_pk_bf16_f32 v1, v8, v1
	v_lshlrev_b32_e32 v8, 16, v2
	v_mul_f32_e32 v9, 0xbfb8aa3b, v8
	v_exp_f32_e32 v9, v9
	v_and_b32_e32 v2, 0xffff0000, v2
	v_add_f32_e32 v9, 1.0, v9
	v_rcp_f32_e32 v10, v9
	s_nop 0
	v_mul_f32_e32 v8, v8, v10
	v_mul_f32_e32 v6, v8, v6
	v_mul_f32_e32 v8, 0xbfb8aa3b, v2
	v_exp_f32_e32 v8, v8
	s_nop 0
	v_add_f32_e32 v8, 1.0, v8
	v_rcp_f32_e32 v9, v8
	s_nop 0
	v_mul_f32_e32 v2, v2, v9
	v_mul_f32_e32 v2, v2, v7
	v_cvt_pk_bf16_f32 v2, v6, v2
	v_lshlrev_b32_e32 v6, 16, v3
	v_mul_f32_e32 v7, 0xbfb8aa3b, v6
	v_exp_f32_e32 v7, v7
	v_and_b32_e32 v3, 0xffff0000, v3
	v_add_f32_e32 v7, 1.0, v7
	v_rcp_f32_e32 v8, v7
	s_nop 0
	v_mul_f32_e32 v6, v6, v8
	v_mul_f32_e32 v4, v6, v4
	v_mul_f32_e32 v6, 0xbfb8aa3b, v3
	v_exp_f32_e32 v6, v6
	s_nop 0
	v_add_f32_e32 v6, 1.0, v6
	v_rcp_f32_e32 v7, v6
	s_nop 0
	v_mul_f32_e32 v3, v3, v7
	v_mul_f32_e32 v3, v3, v5
	v_cvt_pk_bf16_f32 v3, v4, v3
	global_store_dwordx4 v[64:65], v[0:3], off offset:16
	v_pk_mul_f32 v[10:11], v[26:27], v[22:23] op_sel_hi:[1,0]
	v_pk_mul_f32 v[8:9], v[24:25], v[22:23] op_sel_hi:[1,0]
	s_nop 0
	v_mov_b64_e32 v[0:1], v[172:173]
	v_mov_b64_e32 v[2:3], v[174:175]
	v_mov_b64_e32 v[32:33], v[200:201]
	v_mov_b64_e32 v[34:35], v[202:203]
	v_mov_b64_e32 v[4:5], v[196:197]
	v_mov_b64_e32 v[6:7], v[198:199]
	v_pk_mul_f32 v[10:11], v[4:5], v[10:11]
	v_pk_mul_f32 v[8:9], v[6:7], v[8:9]
	v_pk_mul_f32 v[6:7], v[28:29], v[22:23] op_sel_hi:[1,0]
	v_pk_mul_f32 v[4:5], v[30:31], v[22:23] op_sel_hi:[1,0]
	v_lshlrev_b32_e32 v23, 16, v0
	v_mul_f32_e32 v24, 0xbfb8aa3b, v23
	v_exp_f32_e32 v24, v24
	v_and_b32_e32 v0, 0xffff0000, v0
	v_pk_mul_f32 v[6:7], v[6:7], v[32:33]
	v_pk_mul_f32 v[4:5], v[4:5], v[34:35]
	v_add_f32_e32 v24, 1.0, v24
	v_rcp_f32_e32 v25, v24
	s_nop 0
	v_mul_f32_e32 v23, v23, v25
	v_mul_f32_e32 v10, v10, v23
	v_mul_f32_e32 v23, 0xbfb8aa3b, v0
	v_exp_f32_e32 v23, v23
	s_nop 0
	v_add_f32_e32 v23, 1.0, v23
	v_rcp_f32_e32 v24, v23
	s_nop 0
	v_mul_f32_e32 v0, v0, v24
	v_mul_f32_e32 v0, v11, v0
	v_cvt_pk_bf16_f32 v0, v10, v0
	v_lshlrev_b32_e32 v10, 16, v1
	v_mul_f32_e32 v11, 0xbfb8aa3b, v10
	v_exp_f32_e32 v11, v11
	v_and_b32_e32 v1, 0xffff0000, v1
	v_add_f32_e32 v11, 1.0, v11
	v_rcp_f32_e32 v23, v11
	s_nop 0
	v_mul_f32_e32 v10, v10, v23
	v_mul_f32_e32 v8, v8, v10
; __device__ __forceinline__ unsigned cvt_pk_bf16(float lo, float hi) { unsigned r; asm volatile("v_cvt_pk_bf16_f32 %0, %1, %2" : "=v"(r) : "v"(lo), "v"(hi)); return r; }
; __device__ __forceinline__ float bflo(unsigned w) { return __uint_as_float(w << 16); }
; __device__ __forceinline__ float bfhi(unsigned w) { return __uint_as_float(w & 0xffff0000u); }
; __device__ __forceinline__ float silu_f(float z) { return z / (1.0f + __expf(-z)); }
; __device__ __forceinline__ void attn_unit(LAS unsigned char* lds, const bf16_t* PROJ, bf16_t* OCAT, const float* subg, float lam, float oml, int b, int h, int qb) {
;     ...
;         for (int i = 0; i < 4; ++i) {
;             const u32x4 z = *(const u32x4*)(zp + 8 * i); const f32x4 ga = *(const f32x4*)(gp + 8 * i), gb = *(const f32x4*)(gp + 8 * i + 4);
;             const f32x4 xa = a[2 * i] * rs * ga, xb = a[2 * i + 1] * rs * gb;
;             u32x4 w; w.x = cvt_pk_bf16(xa.x * silu_f(bflo(z.x)), xa.y * silu_f(bfhi(z.x))); w.y = cvt_pk_bf16(xa.z * silu_f(bflo(z.y)), xa.w * silu_f(bfhi(z.y)));
;             w.z = cvt_pk_bf16(xb.x * silu_f(bflo(z.z)), xb.y * silu_f(bfhi(z.z))); w.w = cvt_pk_bf16(xb.z * silu_f(bflo(z.w)), xb.w * silu_f(bfhi(z.w)));
;             *(u32x4*)(op + 8 * i) = w;
;         }
;     }
;     __syncthreads();
	v_mul_f32_e32 v10, 0xbfb8aa3b, v1
	v_exp_f32_e32 v10, v10
	s_nop 0
	v_add_f32_e32 v10, 1.0, v10
	v_rcp_f32_e32 v11, v10
	s_nop 0
	v_mul_f32_e32 v1, v1, v11
	v_mul_f32_e32 v1, v9, v1
	v_cvt_pk_bf16_f32 v1, v8, v1
	v_lshlrev_b32_e32 v8, 16, v2
	v_mul_f32_e32 v9, 0xbfb8aa3b, v8
	v_exp_f32_e32 v9, v9
	v_and_b32_e32 v2, 0xffff0000, v2
	v_add_f32_e32 v9, 1.0, v9
	v_rcp_f32_e32 v10, v9
	s_nop 0
	v_mul_f32_e32 v8, v8, v10
	v_mul_f32_e32 v6, v6, v8
	v_mul_f32_e32 v8, 0xbfb8aa3b, v2
	v_exp_f32_e32 v8, v8
	s_nop 0
	v_add_f32_e32 v8, 1.0, v8
	v_rcp_f32_e32 v9, v8
	s_nop 0
	v_mul_f32_e32 v2, v2, v9
	v_mul_f32_e32 v2, v7, v2
	v_cvt_pk_bf16_f32 v2, v6, v2
	v_lshlrev_b32_e32 v6, 16, v3
	v_mul_f32_e32 v7, 0xbfb8aa3b, v6
	v_exp_f32_e32 v7, v7
	v_and_b32_e32 v3, 0xffff0000, v3
	v_add_f32_e32 v7, 1.0, v7
	v_rcp_f32_e32 v8, v7
	s_nop 0
	v_mul_f32_e32 v6, v6, v8
	v_mul_f32_e32 v4, v4, v6
	v_mul_f32_e32 v6, 0xbfb8aa3b, v3
	v_exp_f32_e32 v6, v6
	v_pk_mul_f32 v[14:15], v[14:15], v[22:23] op_sel_hi:[1,0]
	v_add_f32_e32 v6, 1.0, v6
	v_rcp_f32_e32 v7, v6
	s_nop 0
	v_mul_f32_e32 v3, v3, v7
	v_mul_f32_e32 v3, v5, v3
	v_cvt_pk_bf16_f32 v3, v4, v3
	global_store_dwordx4 v[64:65], v[0:3], off offset:32
	v_pk_mul_f32 v[8:9], v[16:17], v[22:23] op_sel_hi:[1,0]
	s_nop 0
	v_mov_b64_e32 v[0:1], v[176:177]
	v_mov_b64_e32 v[2:3], v[178:179]
	v_mov_b64_e32 v[10:11], v[208:209]
	v_mov_b64_e32 v[12:13], v[210:211]
	v_mov_b64_e32 v[4:5], v[204:205]
	v_mov_b64_e32 v[6:7], v[206:207]
	v_pk_mul_f32 v[14:15], v[14:15], v[4:5]
	v_pk_mul_f32 v[8:9], v[8:9], v[6:7]
	v_pk_mul_f32 v[6:7], v[20:21], v[22:23] op_sel_hi:[1,0]
	v_pk_mul_f32 v[4:5], v[18:19], v[22:23] op_sel_hi:[1,0]
	v_pk_mul_f32 v[6:7], v[6:7], v[10:11]
	v_lshlrev_b32_e32 v10, 16, v0
	v_mul_f32_e32 v11, 0xbfb8aa3b, v10
	v_exp_f32_e32 v11, v11
	v_pk_mul_f32 v[4:5], v[4:5], v[12:13]
	v_and_b32_e32 v0, 0xffff0000, v0
	v_add_f32_e32 v11, 1.0, v11
	v_rcp_f32_e32 v12, v11
	s_nop 0
	v_mul_f32_e32 v10, v10, v12
	v_mul_f32_e32 v11, 0xbfb8aa3b, v0
	v_exp_f32_e32 v11, v11
	v_mul_f32_e32 v10, v14, v10
	v_add_f32_e32 v11, 1.0, v11
	v_rcp_f32_e32 v12, v11
	s_nop 0
	v_mul_f32_e32 v0, v0, v12
	v_mul_f32_e32 v0, v15, v0
	v_cvt_pk_bf16_f32 v0, v10, v0
	v_lshlrev_b32_e32 v10, 16, v1
	v_mul_f32_e32 v11, 0xbfb8aa3b, v10
	v_exp_f32_e32 v11, v11
	v_and_b32_e32 v1, 0xffff0000, v1
	v_add_f32_e32 v11, 1.0, v11
	v_rcp_f32_e32 v12, v11
	s_nop 0
	v_mul_f32_e32 v10, v10, v12
	v_mul_f32_e32 v8, v8, v10
	v_mul_f32_e32 v10, 0xbfb8aa3b, v1
	v_exp_f32_e32 v10, v10
	s_nop 0
	v_add_f32_e32 v10, 1.0, v10
	v_rcp_f32_e32 v11, v10
	s_nop 0
	v_mul_f32_e32 v1, v1, v11
	v_mul_f32_e32 v1, v9, v1
	v_cvt_pk_bf16_f32 v1, v8, v1
	v_lshlrev_b32_e32 v8, 16, v2
	v_mul_f32_e32 v9, 0xbfb8aa3b, v8
	v_exp_f32_e32 v9, v9
	v_and_b32_e32 v2, 0xffff0000, v2
	v_add_f32_e32 v9, 1.0, v9
	v_rcp_f32_e32 v10, v9
	s_nop 0
	v_mul_f32_e32 v8, v8, v10
	v_mul_f32_e32 v6, v6, v8
	v_mul_f32_e32 v8, 0xbfb8aa3b, v2
	v_exp_f32_e32 v8, v8
	s_nop 0
	v_add_f32_e32 v8, 1.0, v8
	v_rcp_f32_e32 v9, v8
	s_nop 0
	v_mul_f32_e32 v2, v2, v9
	v_mul_f32_e32 v2, v7, v2
	v_cvt_pk_bf16_f32 v2, v6, v2
	v_lshlrev_b32_e32 v6, 16, v3
	v_mul_f32_e32 v7, 0xbfb8aa3b, v6
	v_exp_f32_e32 v7, v7
	v_and_b32_e32 v3, 0xffff0000, v3
	v_add_f32_e32 v7, 1.0, v7
	v_rcp_f32_e32 v8, v7
	s_nop 0
	v_mul_f32_e32 v6, v6, v8
	v_mul_f32_e32 v4, v4, v6
	v_mul_f32_e32 v6, 0xbfb8aa3b, v3
	v_exp_f32_e32 v6, v6
	s_nop 0
	v_add_f32_e32 v6, 1.0, v6
	v_rcp_f32_e32 v7, v6
	s_nop 0
	v_mul_f32_e32 v3, v3, v7
	v_mul_f32_e32 v3, v5, v3
	v_cvt_pk_bf16_f32 v3, v4, v3
	global_store_dwordx4 v[64:65], v[0:3], off offset:48
	s_barrier
	s_cbranch_scc1 .LBB0_473
